# sgu_unit: norm-gain loads hoisted into the main load batch (removes two dependent memory round trips per unit)
# speedup vs baseline: 1.0066x; 1.0043x over previous
; #define LAS __attribute__((address_space(3)))
; __device__ __forceinline__ void sgu_unit(int chunk, int g, const bf16_t* ZUV, const float* SS2, const float* gn, const bf16_t* SGUW, const float* bs, bf16_t* MIX, LAS unsigned char* lds) {
;     ...
;     const int sr = tid & 127, qd = __builtin_amdgcn_readfirstlane(tid >> 7);
;     const bf16_t* zp = ZUV + (size_t)(r0 + sr) * 2048 + 1024 + g * 128 + qd * 32;
;     const bf16_t* wp = SGUW + (size_t)(g * 128 + t) * 128 + 8 * hi;
;     const bf16_t* zup = ZUV + (size_t)(r0 + t) * 2048 + g * 128;
;     u32x4 w[4]; f32x4 sq[4]; bf16x8 wvv[8]; u32x2 zav[4], zbv[4];
; #pragma unroll
;     for (int j = 0; j < 4; ++j) { w[j] = *(const u32x4*)(zp + j * 8); sq[j] = *(const f32x4*)(SS2 + (size_t)(r0 + sr) * 16 + 4 * j); }
; #pragma unroll
;     for (int ks = 0; ks < 8; ++ks) wvv[ks] = *(const bf16x8*)(wp + 16 * ks);
; #pragma unroll
;     for (int j = 0; j < 4; ++j) { zav[j] = *(const u32x2*)(zup + 32 * cb0 + 8 * j + 4 * hi); zbv[j] = *(const u32x2*)(zup + 32 * cb0 + 8 * j + 4 * hi + 32); }
;     const float bt = bs[g * 128 + t];
;     asm volatile("" : "+v"(w[0]), "+v"(w[1]), "+v"(w[2]), "+v"(w[3]), "+v"(sq[0]), "+v"(sq[1]), "+v"(sq[2]), "+v"(sq[3]),
;                  "+v"(wvv[0]), "+v"(wvv[1]), "+v"(wvv[2]), "+v"(wvv[3]), "+v"(wvv[4]), "+v"(wvv[5]), "+v"(wvv[6]), "+v"(wvv[7]),
;                  "+v"(zav[0]), "+v"(zav[1]), "+v"(zav[2]), "+v"(zav[3]), "+v"(zbv[0]), "+v"(zbv[1]), "+v"(zbv[2]), "+v"(zbv[3]) :: "memory");
;     {
;         const float sm = ((sq[0].x + sq[0].y) + (sq[0].z + sq[0].w)) + ((sq[1].x + sq[1].y) + (sq[1].z + sq[1].w)) + ((sq[2].x + sq[2].y) + (sq[2].z + sq[2].w)) + ((sq[3].x + sq[3].y) + (sq[3].z + sq[3].w));
;         const float rs = rsqrtf(sm * (1.0f / 1024.0f) + EPS);
; #pragma unroll
;         for (int j = 0; j < 4; ++j) {
;             const float* gp = gn + g * 128 + qd * 32 + j * 8; const f32x4 g0 = *(const f32x4*)gp, g1 = *(const f32x4*)(gp + 4);
;             const float v[8] = {bf_lo(w[j].x) * rs * g0.x, bf_hi(w[j].x) * rs * g0.y, bf_lo(w[j].y) * rs * g0.z, bf_hi(w[j].y) * rs * g0.w, bf_lo(w[j].z) * rs * g1.x, bf_hi(w[j].z) * rs * g1.y, bf_lo(w[j].w) * rs * g1.z, bf_hi(w[j].w) * rs * g1.w};
;             LAS bf16_t* zt = ZT + (qd * 32 + j * 8) * 136 + sr;
; #pragma unroll
;             for (int e = 0; e < 8; ++e) zt[e * 136] = (bf16_t)(pk_bf16(v[e], 0.f) & 0xffffu);
;         }
;     }
.LBB0_249:
	v_mov_b32_e32 v0, v198
	v_mov_b32_e32 v2, s9
	v_readfirstlane_b32 s0, v0
	s_lshr_b32 s4, s0, 1
	v_and_b32_e32 v30, 31, v0
	s_and_b32 s4, s4, 0x60
	v_or_b32_e32 v6, s4, v30
	s_movk_i32 s4, 0x7f
	v_bfi_b32 v2, s4, v0, v2
	s_and_b32 s1, s9, 0xffffff80
	v_ashrrev_i32_e32 v3, 31, v2
	v_lshlrev_b64 v[4:5], 12, v[2:3]
	s_and_b32 s6, s8, 0x380
	s_ashr_i32 s0, s0, 2
	v_or_b32_e32 v80, s1, v6
	v_lshl_add_u64 v[4:5], s[54:55], 0, v[4:5]
	s_lshl_b32 s50, s6, 1
	s_and_b32 s4, s0, 0xffffffe0
	v_ashrrev_i32_e32 v81, 31, v80
	v_lshl_add_u64 v[4:5], v[4:5], 0, s[50:51]
	s_ashr_i32 s5, s4, 31
	v_or_b32_e32 v36, s6, v6
	v_lshlrev_b64 v[6:7], 12, v[80:81]
	v_lshl_add_u64 v[4:5], s[4:5], 1, v[4:5]
	v_lshl_add_u64 v[34:35], s[54:55], 0, v[6:7]
	v_lshlrev_b64 v[2:3], 6, v[2:3]
	s_andn2_b32 s0, s0, 63
	v_bfe_u32 v65, v0, 5, 1
	v_lshl_add_u64 v[2:3], s[16:17], 0, v[2:3]
	global_load_dwordx4 v[6:9], v[4:5], off offset:2096
	global_load_dwordx4 v[10:13], v[4:5], off offset:2080
	global_load_dwordx4 v[14:17], v[4:5], off offset:2064
	global_load_dwordx4 v[18:21], v[4:5], off offset:2048
	v_lshl_add_u64 v[238:239], v[4:5], 0, s[98:99]
	global_load_dwordx4 v[22:25], v[2:3], off offset:48
	global_load_dwordx4 v[26:29], v[2:3], off offset:32
	global_load_dwordx4 v[82:85], v[2:3], off offset:16
	global_load_dwordx4 v[86:89], v[2:3], off
	v_lshl_add_u64 v[240:241], v[2:3], 0, s[100:101]
	v_lshl_add_u64 v[4:5], v[34:35], 0, s[50:51]
	s_ashr_i32 s1, s0, 31
	v_and_b32_e32 v31, 0x7f, v0
	v_lshlrev_b32_e32 v0, 8, v36
	v_lshlrev_b32_e32 v32, 3, v65
	v_mov_b32_e32 v33, v1
	v_lshl_add_u64 v[4:5], s[0:1], 1, v[4:5]
	v_lshl_add_u64 v[2:3], s[12:13], 0, v[0:1]
	v_lshlrev_b32_e32 v0, 4, v65
	v_lshl_add_u64 v[4:5], v[4:5], 0, v[32:33]
	v_lshl_add_u64 v[2:3], v[2:3], 0, v[0:1]
	v_lshl_add_u64 v[242:243], v[4:5], 0, s[98:99]
	global_load_dwordx2 v[78:79], v[4:5], off
	global_load_dwordx2 v[76:77], v[4:5], off offset:64
	global_load_dwordx2 v[74:75], v[4:5], off offset:16
	global_load_dwordx2 v[72:73], v[4:5], off offset:80
	global_load_dwordx2 v[70:71], v[4:5], off offset:32
	global_load_dwordx2 v[68:69], v[4:5], off offset:96
	global_load_dwordx2 v[66:67], v[4:5], off offset:48
	global_load_dwordx2 v[62:63], v[4:5], off offset:112
	v_lshlrev_b32_e32 v4, 2, v36
	global_load_dword v64, v4, s[22:23]
	global_load_dwordx4 v[34:37], v[2:3], off offset:224
	global_load_dwordx4 v[38:41], v[2:3], off offset:192
	global_load_dwordx4 v[42:45], v[2:3], off offset:160
	global_load_dwordx4 v[46:49], v[2:3], off offset:128
	global_load_dwordx4 v[50:53], v[2:3], off offset:96
	global_load_dwordx4 v[54:57], v[2:3], off offset:64
	global_load_dwordx4 v[58:61], v[2:3], off offset:32
	s_nop 0
	global_load_dwordx4 v[2:5], v[2:3], off
	s_lshl_b32 s1, s6, 2
	s_add_u32 s1, s14, s1
	s_addc_u32 s11, s15, 0
	s_lshl_b64 s[6:7], s[4:5], 2
	s_add_u32 s6, s1, s6
	s_addc_u32 s7, s11, s7
	s_mul_i32 s1, s4, 0x110
	s_add_i32 s1, s1, 0
	v_lshl_add_u32 v31, v31, 1, s1
	s_add_i32 s10, s10, s34
	s_add_i32 s9, s9, s96
	s_add_i32 s8, s8, s20
	s_cmpk_gt_i32 s10, 0xfff
	global_load_dwordx4 v[206:209], v1, s[6:7]
	global_load_dwordx4 v[210:213], v1, s[6:7] offset:16
	global_load_dwordx4 v[214:217], v1, s[6:7] offset:32
	global_load_dwordx4 v[218:221], v1, s[6:7] offset:48
	global_load_dwordx4 v[222:225], v1, s[6:7] offset:64
	global_load_dwordx4 v[226:229], v1, s[6:7] offset:80
	global_load_dwordx4 v[230:233], v1, s[6:7] offset:96
	global_load_dwordx4 v[234:237], v1, s[6:7] offset:112
	s_waitcnt vmcnt(0)
	s_nop 0
	v_mov_b32_e32 v32, v87
	v_mov_b32_e32 v33, v88
	v_mov_b32_e32 v87, v89
	v_pk_add_f32 v[32:33], v[32:33], v[86:87]
	v_mov_b32_e32 v86, v83
	v_mov_b32_e32 v87, v84
	v_mov_b32_e32 v83, v85
	v_pk_add_f32 v[82:83], v[86:87], v[82:83]
	v_pk_add_f32 v[32:33], v[32:33], v[32:33] op_sel_hi:[0,1]
	v_pk_add_f32 v[82:83], v[82:83], v[82:83] op_sel_hi:[0,1]
	v_add_f32_e32 v27, v26, v27
	v_add_f32_e32 v29, v28, v29
	v_mov_b32_e32 v26, v22
	v_mov_b32_e32 v28, v23
	v_mov_b32_e32 v32, v24
	v_mov_b32_e32 v82, v25
	v_pk_add_f32 v[22:23], v[26:27], v[28:29]
	v_pk_add_f32 v[24:25], v[32:33], v[82:83]
	v_lshlrev_b32_e32 v33, 16, v18
	v_pk_add_f32 v[22:23], v[22:23], v[24:25]
	v_and_b32_e32 v18, 0xffff0000, v18
	v_add_f32_e32 v22, v22, v23
	v_fmamk_f32 v22, v22, 0x3a800000, v201
	v_cmp_gt_f32_e32 vcc, s57, v22
	v_mul_f32_e32 v23, 0x4b800000, v22
	s_nop 0
	v_cndmask_b32_e32 v22, v22, v23, vcc
	v_rsq_f32_e32 v22, v22
	s_nop 0
	v_mul_f32_e32 v23, 0x45800000, v22
	v_cndmask_b32_e32 v32, v22, v23, vcc
	v_mul_f32_e32 v33, v32, v33
	v_mul_f32_e32 v18, v32, v18
	v_mul_f32_e32 v33, v206, v33
	v_lshlrev_b32_e32 v86, 16, v19
	v_mul_f32_e32 v18, v207, v18
	v_mul_f32_e32 v86, v32, v86
	v_and_b32_e32 v19, 0xffff0000, v19
	v_mul_f32_e32 v86, v208, v86
	v_mul_f32_e32 v19, v32, v19
	v_lshlrev_b32_e32 v87, 16, v20
	v_and_b32_e32 v20, 0xffff0000, v20
	v_cvt_pk_bf16_f32 v18, v18, s0
	v_mul_f32_e32 v19, v209, v19
	v_mul_f32_e32 v87, v32, v87
	v_mul_f32_e32 v20, v32, v20
	ds_write_b16 v31, v18 offset:272
	v_cvt_pk_bf16_f32 v18, v86, s0
	v_mul_f32_e32 v82, v210, v87
	v_mul_f32_e32 v20, v211, v20
	v_lshlrev_b32_e32 v83, 16, v21
	ds_write_b16 v31, v18 offset:544
	v_cvt_pk_bf16_f32 v18, v19, s0
	v_mul_f32_e32 v83, v32, v83
	v_and_b32_e32 v21, 0xffff0000, v21
	ds_write_b16 v31, v18 offset:816
	v_cvt_pk_bf16_f32 v18, v82, s0
	v_mul_f32_e32 v83, v212, v83
	v_mul_f32_e32 v21, v32, v21
	ds_write_b16 v31, v18 offset:1088
	v_cvt_pk_bf16_f32 v18, v20, s0
	v_mul_f32_e32 v21, v213, v21
	ds_write_b16 v31, v18 offset:1360
	v_cvt_pk_bf16_f32 v18, v83, s0
	ds_write_b16 v31, v18 offset:1632
	v_cvt_pk_bf16_f32 v18, v21, s0
	ds_write_b16 v31, v18 offset:1904
; #define LAS __attribute__((address_space(3)))
; __device__ __forceinline__ unsigned pk_bf16(float lo, float hi) { const f32x2_t v = {lo, hi}; const bf16x2_t b = __builtin_convertvector(v, bf16x2_t); return __builtin_bit_cast(unsigned, b); }
; __device__ __forceinline__ float bf_lo(unsigned w) { return __uint_as_float(w << 16); }
; __device__ __forceinline__ float bf_hi(unsigned w) { return __uint_as_float(w & 0xffff0000u); }
; __device__ __forceinline__ void sgu_unit(int chunk, int g, const bf16_t* ZUV, const float* SS2, const float* gn, const bf16_t* SGUW, const float* bs, bf16_t* MIX, LAS unsigned char* lds) {
;     ...
; #pragma unroll
;         for (int j = 0; j < 4; ++j) {
;             const float* gp = gn + g * 128 + qd * 32 + j * 8; const f32x4 g0 = *(const f32x4*)gp, g1 = *(const f32x4*)(gp + 4);
;             const float v[8] = {bf_lo(w[j].x) * rs * g0.x, bf_hi(w[j].x) * rs * g0.y, bf_lo(w[j].y) * rs * g0.z, bf_hi(w[j].y) * rs * g0.w, bf_lo(w[j].z) * rs * g1.x, bf_hi(w[j].z) * rs * g1.y, bf_lo(w[j].w) * rs * g1.z, bf_hi(w[j].w) * rs * g1.w};
;             LAS bf16_t* zt = ZT + (qd * 32 + j * 8) * 136 + sr;
; #pragma unroll
;             for (int e = 0; e < 8; ++e) zt[e * 136] = (bf16_t)(pk_bf16(v[e], 0.f) & 0xffffu);
;         }
;     }
;     __syncthreads();
	v_lshlrev_b32_e32 v18, 16, v14
	v_and_b32_e32 v14, 0xffff0000, v14
	v_mul_f32_e32 v14, v32, v14
	v_lshlrev_b32_e32 v19, 16, v15
	v_mul_f32_e32 v14, v215, v14
	v_mul_f32_e32 v19, v32, v19
	v_and_b32_e32 v15, 0xffff0000, v15
	v_mul_f32_e32 v19, v216, v19
	v_mul_f32_e32 v15, v32, v15
	v_lshlrev_b32_e32 v20, 16, v16
	v_cvt_pk_bf16_f32 v14, v14, s0
	v_mul_f32_e32 v15, v217, v15
	v_mul_f32_e32 v20, v32, v20
	v_and_b32_e32 v16, 0xffff0000, v16
	ds_write_b16 v31, v14 offset:2448
	v_cvt_pk_bf16_f32 v14, v19, s0
	v_mul_f32_e32 v20, v218, v20
	v_mul_f32_e32 v16, v32, v16
	v_lshlrev_b32_e32 v21, 16, v17
	ds_write_b16 v31, v14 offset:2720
	v_cvt_pk_bf16_f32 v14, v15, s0
	v_mul_f32_e32 v16, v219, v16
	v_mul_f32_e32 v21, v32, v21
	v_and_b32_e32 v17, 0xffff0000, v17
	ds_write_b16 v31, v14 offset:2992
	v_cvt_pk_bf16_f32 v14, v20, s0
	v_mul_f32_e32 v18, v32, v18
	v_mul_f32_e32 v21, v220, v21
	v_mul_f32_e32 v17, v32, v17
	ds_write_b16 v31, v14 offset:3264
	v_cvt_pk_bf16_f32 v14, v16, s0
	v_mul_f32_e32 v18, v214, v18
	v_mul_f32_e32 v17, v221, v17
	ds_write_b16 v31, v14 offset:3536
	v_cvt_pk_bf16_f32 v14, v21, s0
	v_cvt_pk_bf16_f32 v33, v33, s0
	v_cvt_pk_bf16_f32 v18, v18, s0
	ds_write_b16 v31, v14 offset:3808
	v_cvt_pk_bf16_f32 v14, v17, s0
	ds_write_b16 v31, v33
	ds_write_b16 v31, v18 offset:2176
	ds_write_b16 v31, v14 offset:4080
	v_lshlrev_b32_e32 v33, 16, v10
	v_and_b32_e32 v10, 0xffff0000, v10
	v_mul_f32_e32 v10, v32, v10
	v_mul_f32_e32 v33, v32, v33
	s_waitcnt vmcnt(0)
	v_mul_f32_e32 v10, v10, v223
	v_lshlrev_b32_e32 v27, 16, v11
	v_mul_f32_e32 v27, v32, v27
	v_and_b32_e32 v11, 0xffff0000, v11
	v_mul_f32_e32 v27, v27, v224
	v_mul_f32_e32 v11, v32, v11
	v_lshlrev_b32_e32 v28, 16, v12
	v_and_b32_e32 v12, 0xffff0000, v12
	v_cvt_pk_bf16_f32 v10, v10, s0
	v_mul_f32_e32 v11, v11, v225
	v_mul_f32_e32 v28, v32, v28
	v_mul_f32_e32 v12, v32, v12
	ds_write_b16 v31, v10 offset:4624
	v_cvt_pk_bf16_f32 v10, v27, s0
	v_mul_f32_e32 v22, v28, v226
	v_mul_f32_e32 v12, v12, v227
	v_lshlrev_b32_e32 v23, 16, v13
	ds_write_b16 v31, v10 offset:4896
	v_cvt_pk_bf16_f32 v10, v11, s0
	v_mul_f32_e32 v23, v32, v23
	v_and_b32_e32 v13, 0xffff0000, v13
	ds_write_b16 v31, v10 offset:5168
	v_cvt_pk_bf16_f32 v10, v22, s0
	v_mul_f32_e32 v23, v23, v228
	v_mul_f32_e32 v13, v32, v13
	ds_write_b16 v31, v10 offset:5440
	v_cvt_pk_bf16_f32 v10, v12, s0
	v_mul_f32_e32 v13, v13, v229
	ds_write_b16 v31, v10 offset:5712
	v_cvt_pk_bf16_f32 v10, v23, s0
	ds_write_b16 v31, v10 offset:5984
	v_cvt_pk_bf16_f32 v10, v13, s0
	ds_write_b16 v31, v10 offset:6256
	v_lshlrev_b32_e32 v10, 16, v6
	v_and_b32_e32 v6, 0xffff0000, v6
	v_mul_f32_e32 v6, v32, v6
	v_lshlrev_b32_e32 v11, 16, v7
	v_mul_f32_e32 v6, v6, v231
	v_mul_f32_e32 v11, v32, v11
	v_and_b32_e32 v7, 0xffff0000, v7
	v_mul_f32_e32 v11, v11, v232
	v_mul_f32_e32 v7, v32, v7
	v_lshlrev_b32_e32 v12, 16, v8
	v_cvt_pk_bf16_f32 v6, v6, s0
	v_mul_f32_e32 v7, v7, v233
	v_mul_f32_e32 v12, v32, v12
	v_and_b32_e32 v8, 0xffff0000, v8
	ds_write_b16 v31, v6 offset:6800
	v_cvt_pk_bf16_f32 v6, v11, s0
	v_mul_f32_e32 v12, v12, v234
	v_mul_f32_e32 v8, v32, v8
	v_lshlrev_b32_e32 v13, 16, v9
	ds_write_b16 v31, v6 offset:7072
	v_cvt_pk_bf16_f32 v6, v7, s0
	v_mul_f32_e32 v8, v8, v235
	v_mul_f32_e32 v13, v32, v13
	v_and_b32_e32 v9, 0xffff0000, v9
	ds_write_b16 v31, v6 offset:7344
	v_cvt_pk_bf16_f32 v6, v12, s0
	v_mul_f32_e32 v13, v13, v236
	v_mul_f32_e32 v9, v32, v9
	ds_write_b16 v31, v6 offset:7616
	v_cvt_pk_bf16_f32 v6, v8, s0
	v_mul_f32_e32 v9, v9, v237
	ds_write_b16 v31, v6 offset:7888
	v_cvt_pk_bf16_f32 v6, v13, s0
	ds_write_b16 v31, v6 offset:8160
	v_cvt_pk_bf16_f32 v6, v9, s0
	v_mul_f32_e32 v10, v32, v10
	ds_write_b16 v31, v6 offset:8432
	v_or_b32_e32 v6, s0, v30
	v_mul_f32_e32 v26, v33, v222
	v_mul_f32_e32 v10, v10, v230
	v_mul_lo_u32 v6, v6, s21
	v_cvt_pk_bf16_f32 v24, v26, s0
	v_cvt_pk_bf16_f32 v10, v10, s0
	v_add3_u32 v0, 0, v6, v0
	ds_write_b16 v31, v24 offset:4352
	ds_write_b16 v31, v10 offset:6528
	s_waitcnt lgkmcnt(0)
	s_barrier
; #define LAS __attribute__((address_space(3)))
; __device__ __forceinline__ unsigned pk_bf16(float lo, float hi) { const f32x2_t v = {lo, hi}; const bf16x2_t b = __builtin_convertvector(v, bf16x2_t); return __builtin_bit_cast(unsigned, b); }
; __device__ __forceinline__ float bf_lo(unsigned w) { return __uint_as_float(w << 16); }
; __device__ __forceinline__ float bf_hi(unsigned w) { return __uint_as_float(w & 0xffff0000u); }
; __device__ __forceinline__ void sgu_unit(int chunk, int g, const bf16_t* ZUV, const float* SS2, const float* gn, const bf16_t* SGUW, const float* bs, bf16_t* MIX, LAS unsigned char* lds) {
;     ...
;     f32x16 d0, d1;
; #pragma unroll
;     for (int r = 0; r < 16; ++r) { d0[r] = 0.f; d1[r] = 0.f; }
; #pragma unroll
;     for (int ks = 0; ks < 8; ++ks) {
;         const bf16x8 z0 = *(const LAS bf16x8*)(ZT + (32 * cb0 + q32) * 136 + 16 * ks + 8 * hi);
;         const bf16x8 z1 = *(const LAS bf16x8*)(ZT + (32 * (cb0 + 1) + q32) * 136 + 16 * ks + 8 * hi);
;         d0 = __builtin_amdgcn_mfma_f32_32x32x16_bf16(z0, wvv[ks], d0, 0, 0, 0);
;         d1 = __builtin_amdgcn_mfma_f32_32x32x16_bf16(z1, wvv[ks], d1, 0, 0, 0);
;     }
;     bf16_t* op = MIX + (size_t)(r0 + t) * DM + g * 128;
; #pragma unroll
;     for (int j = 0; j < 4; ++j) {
;         const int c0 = 32 * cb0 + 8 * j + 4 * hi, c1 = c0 + 32;
;         const u32x2 za = zav[j], zb = zbv[j];
;         u32x2 wa, wb;
;         wa.x = pk_bf16(bf_lo(za.x) * (d0[4 * j + 0] + bt), bf_hi(za.x) * (d0[4 * j + 1] + bt)); wa.y = pk_bf16(bf_lo(za.y) * (d0[4 * j + 2] + bt), bf_hi(za.y) * (d0[4 * j + 3] + bt));
;         wb.x = pk_bf16(bf_lo(zb.x) * (d1[4 * j + 0] + bt), bf_hi(zb.x) * (d1[4 * j + 1] + bt)); wb.y = pk_bf16(bf_lo(zb.y) * (d1[4 * j + 2] + bt), bf_hi(zb.y) * (d1[4 * j + 3] + bt));
;         *(u32x2*)(op + c0) = wa; *(u32x2*)(op + c1) = wb;
;     }
;     __syncthreads();
	ds_read_b128 v[6:9], v0 offset:8704
	ds_read_b128 v[10:13], v0
	ds_read_b128 v[82:85], v0 offset:32
	s_waitcnt lgkmcnt(1)
	v_mfma_f32_32x32x16_bf16 v[18:33], v[10:13], v[2:5], 0
	ds_read_b128 v[86:89], v0 offset:8736
	v_mfma_f32_32x32x16_bf16 v[2:17], v[6:9], v[2:5], 0
	s_waitcnt lgkmcnt(1)
	v_mfma_f32_32x32x16_bf16 v[18:33], v[82:85], v[58:61], v[18:33]
	s_waitcnt lgkmcnt(0)
	v_mfma_f32_32x32x16_bf16 v[2:17], v[86:89], v[58:61], v[2:17]
	ds_read_b128 v[58:61], v0 offset:64
	ds_read_b128 v[82:85], v0 offset:8768
	s_waitcnt lgkmcnt(1)
	v_mfma_f32_32x32x16_bf16 v[18:33], v[58:61], v[54:57], v[18:33]
	s_waitcnt lgkmcnt(0)
	v_mfma_f32_32x32x16_bf16 v[2:17], v[82:85], v[54:57], v[2:17]
	ds_read_b128 v[54:57], v0 offset:96
	ds_read_b128 v[58:61], v0 offset:8800
	s_waitcnt lgkmcnt(1)
	v_mfma_f32_32x32x16_bf16 v[18:33], v[54:57], v[50:53], v[18:33]
	s_waitcnt lgkmcnt(0)
	v_mfma_f32_32x32x16_bf16 v[2:17], v[58:61], v[50:53], v[2:17]
	ds_read_b128 v[50:53], v0 offset:128
	ds_read_b128 v[54:57], v0 offset:8832
	s_waitcnt lgkmcnt(1)
	v_mfma_f32_32x32x16_bf16 v[18:33], v[50:53], v[46:49], v[18:33]
	s_waitcnt lgkmcnt(0)
	v_mfma_f32_32x32x16_bf16 v[2:17], v[54:57], v[46:49], v[2:17]
	ds_read_b128 v[46:49], v0 offset:160
	ds_read_b128 v[50:53], v0 offset:8864
	s_waitcnt lgkmcnt(1)
	v_mfma_f32_32x32x16_bf16 v[18:33], v[46:49], v[42:45], v[18:33]
	s_waitcnt lgkmcnt(0)
	v_mfma_f32_32x32x16_bf16 v[2:17], v[50:53], v[42:45], v[2:17]
	ds_read_b128 v[42:45], v0 offset:192
	ds_read_b128 v[46:49], v0 offset:8896
	s_waitcnt lgkmcnt(1)
	v_mfma_f32_32x32x16_bf16 v[18:33], v[42:45], v[38:41], v[18:33]
	s_waitcnt lgkmcnt(0)
	v_mfma_f32_32x32x16_bf16 v[2:17], v[46:49], v[38:41], v[2:17]
	ds_read_b128 v[38:41], v0 offset:224
	ds_read_b128 v[42:45], v0 offset:8928
	s_waitcnt lgkmcnt(1)
	v_mfma_f32_32x32x16_bf16 v[18:33], v[38:41], v[34:37], v[18:33]
	v_lshlrev_b32_e32 v38, 16, v78
	v_and_b32_e32 v39, 0xffff0000, v78
	s_waitcnt lgkmcnt(0)
	v_mfma_f32_32x32x16_bf16 v[2:17], v[42:45], v[34:37], v[2:17]
	s_nop 7
	v_add_f32_e64 v18, v64, v18
	v_add_f32_e64 v19, v64, v19
	v_mul_f32_e64 v18, v18, v38
	v_mul_f32_e64 v19, v19, v39
	v_lshlrev_b32_e32 v38, 16, v79
	v_and_b32_e32 v39, 0xffff0000, v79
	v_pk_add_f32 v[20:21], v[64:65], v[20:21] op_sel_hi:[0,1]
	v_pk_mul_f32 v[20:21], v[20:21], v[38:39]
	v_lshlrev_b64 v[34:35], 11, v[80:81]
	v_cvt_pk_bf16_f32 v18, v18, v19
	v_cvt_pk_bf16_f32 v19, v20, v21
	v_lshlrev_b32_e32 v20, 16, v76
	v_and_b32_e32 v21, 0xffff0000, v76
	v_pk_add_f32 v[2:3], v[64:65], v[2:3] op_sel_hi:[0,1]
	v_lshl_add_u64 v[34:35], s[52:53], 0, v[34:35]
	v_lshl_or_b32 v36, v65, 2, s0
	v_pk_mul_f32 v[2:3], v[2:3], v[20:21]
	v_lshlrev_b32_e32 v20, 16, v77
	v_and_b32_e32 v21, 0xffff0000, v77
	v_pk_add_f32 v[4:5], v[64:65], v[4:5] op_sel_hi:[0,1]
	v_lshl_add_u64 v[34:35], v[34:35], 0, s[50:51]
	v_pk_mul_f32 v[4:5], v[4:5], v[20:21]
	v_ashrrev_i32_e32 v37, 31, v36
	v_cvt_pk_bf16_f32 v2, v2, v3
	v_cvt_pk_bf16_f32 v3, v4, v5
	v_lshl_add_u64 v[4:5], v[36:37], 1, v[34:35]
	global_store_dwordx2 v[4:5], v[18:19], off
	global_store_dwordx2 v[4:5], v[2:3], off offset:64
	v_lshlrev_b32_e32 v2, 16, v74
	v_and_b32_e32 v3, 0xffff0000, v74
	v_pk_add_f32 v[18:19], v[64:65], v[22:23] op_sel_hi:[0,1]
	v_pk_mul_f32 v[2:3], v[18:19], v[2:3]
	v_lshlrev_b32_e32 v18, 16, v75
	v_and_b32_e32 v19, 0xffff0000, v75
	v_pk_add_f32 v[20:21], v[64:65], v[24:25] op_sel_hi:[0,1]
	v_pk_mul_f32 v[18:19], v[20:21], v[18:19]
	v_cvt_pk_bf16_f32 v2, v2, v3
	v_cvt_pk_bf16_f32 v3, v18, v19
	v_lshlrev_b32_e32 v18, 16, v72
	v_and_b32_e32 v19, 0xffff0000, v72
	v_pk_add_f32 v[6:7], v[64:65], v[6:7] op_sel_hi:[0,1]
	v_pk_mul_f32 v[6:7], v[6:7], v[18:19]
	v_lshlrev_b32_e32 v18, 16, v73
	v_and_b32_e32 v19, 0xffff0000, v73
	v_pk_add_f32 v[8:9], v[64:65], v[8:9] op_sel_hi:[0,1]
	v_pk_mul_f32 v[8:9], v[8:9], v[18:19]
	v_cvt_pk_bf16_f32 v6, v6, v7
	v_cvt_pk_bf16_f32 v7, v8, v9
	global_store_dwordx2 v[4:5], v[2:3], off offset:16
	global_store_dwordx2 v[4:5], v[6:7], off offset:80
	v_lshlrev_b32_e32 v2, 16, v70
	v_and_b32_e32 v3, 0xffff0000, v70
	v_pk_add_f32 v[6:7], v[64:65], v[26:27] op_sel_hi:[0,1]
	v_pk_mul_f32 v[2:3], v[6:7], v[2:3]
	v_lshlrev_b32_e32 v6, 16, v71
	v_and_b32_e32 v7, 0xffff0000, v71
	v_pk_add_f32 v[8:9], v[64:65], v[28:29] op_sel_hi:[0,1]
	v_pk_mul_f32 v[6:7], v[8:9], v[6:7]
	v_cvt_pk_bf16_f32 v2, v2, v3
	v_cvt_pk_bf16_f32 v3, v6, v7
	v_lshlrev_b32_e32 v6, 16, v68
	v_and_b32_e32 v7, 0xffff0000, v68
	v_pk_add_f32 v[8:9], v[64:65], v[10:11] op_sel_hi:[0,1]
	v_pk_mul_f32 v[6:7], v[8:9], v[6:7]
	v_lshlrev_b32_e32 v8, 16, v69
	v_and_b32_e32 v9, 0xffff0000, v69
	v_pk_add_f32 v[10:11], v[64:65], v[12:13] op_sel_hi:[0,1]
	v_pk_mul_f32 v[8:9], v[10:11], v[8:9]
	v_cvt_pk_bf16_f32 v6, v6, v7
	v_cvt_pk_bf16_f32 v7, v8, v9
	global_store_dwordx2 v[4:5], v[2:3], off offset:32
	global_store_dwordx2 v[4:5], v[6:7], off offset:96
	v_lshlrev_b32_e32 v2, 16, v66
	v_and_b32_e32 v3, 0xffff0000, v66
	v_pk_add_f32 v[6:7], v[64:65], v[30:31] op_sel_hi:[0,1]
	v_pk_mul_f32 v[2:3], v[6:7], v[2:3]
	v_lshlrev_b32_e32 v6, 16, v67
	v_and_b32_e32 v7, 0xffff0000, v67
	v_pk_add_f32 v[8:9], v[64:65], v[32:33] op_sel_hi:[0,1]
	v_pk_mul_f32 v[6:7], v[8:9], v[6:7]
	v_cvt_pk_bf16_f32 v2, v2, v3
	v_cvt_pk_bf16_f32 v3, v6, v7
	v_lshlrev_b32_e32 v6, 16, v62
	v_and_b32_e32 v7, 0xffff0000, v62
	v_pk_add_f32 v[8:9], v[64:65], v[14:15] op_sel_hi:[0,1]
	v_pk_mul_f32 v[6:7], v[8:9], v[6:7]
	v_lshlrev_b32_e32 v8, 16, v63
	v_and_b32_e32 v9, 0xffff0000, v63
	v_pk_add_f32 v[10:11], v[64:65], v[16:17] op_sel_hi:[0,1]
	v_pk_mul_f32 v[8:9], v[10:11], v[8:9]
	v_cvt_pk_bf16_f32 v6, v6, v7
	v_cvt_pk_bf16_f32 v7, v8, v9
	global_store_dwordx2 v[4:5], v[2:3], off offset:48
	global_store_dwordx2 v[4:5], v[6:7], off offset:112
	s_barrier
	s_cbranch_scc0 .LBB0_249
